# v25_qk0
# speedup vs baseline: 1.0093x; 1.0028x over previous
; #define LAS __attribute__((address_space(3)))
; __device__ __forceinline__ void phase_attn(const Params& p, int l, LAS unsigned char* lds, int bid, int G, int tid) {
;     ...
;                     const int qb = 2 * qh + blk; int ks0 = 16 * qb - 8; ks0 = ks0 < 0 ? 0 : ks0; ks0 = ks0 > 32 ? 32 : ks0;
;                     f32x4 St[2];
; #pragma unroll
;                     for (int nb = 0; nb < 2; ++nb) { f32x4 a0 = {0.f, 0.f, 0.f, 0.f};
; #pragma unroll
;                         for (int ks = 0; ks < 4; ++ks) { const bf16x8 kf = *(const LAS bf16x8*)(Kt + (ks0 + nb * 16 + fr) * 272 + (ks * 32 + g * 8) * 2);
;                             a0 = __builtin_amdgcn_mfma_f32_16x16x32_bf16(kf, Qf[blk][ks], a0, 0, 0, 0); }
;                         St[nb] = a0; }
;                     const int qc = qb * 16 + fr; int cs = qc - 8; cs = cs < 0 ? 0 : cs; cs = cs > 48 ? 48 : cs;
;                     float mt = -INFINITY;
; #pragma unroll
;                     for (int nb = 0; nb < 2; ++nb)
; #pragma unroll
;                         for (int j = 0; j < 4; ++j) { const int kc = ks0 + nb * 16 + g * 4 + j; const bool ok = (kc >= cs) && (kc < cs + 16);
;                             int dc = kc - qc; dc = dc < -15 ? -15 : dc; dc = dc > 15 ? 15 : dc;
;                             const float sv = ok ? St[nb][j] + rp[dc + 15] : -INFINITY; St[nb][j] = sv; mt = fmaxf(mt, sv); }
;                     mt = fmaxf(mt, __shfl_xor(mt, 16)); mt = fmaxf(mt, __shfl_xor(mt, 32));
;                     const float mnew = fmaxf(mrun[blk], mt), alpha = __expf(mrun[blk] - mnew);
;                     float psum = 0.f;
; #pragma unroll
;                     for (int nb = 0; nb < 2; ++nb)
; #pragma unroll
;                         for (int j = 0; j < 4; ++j) { const float pe = __expf(St[nb][j] - mnew); St[nb][j] = pe; psum += pe; }
;                     lrun[blk] = lrun[blk] * alpha + psum; mrun[blk] = mnew;
;                     u32x4 pv; pv.x = pk2(St[0][0], St[0][1]); pv.y = pk2(St[0][2], St[0][3]); pv.z = pk2(St[1][0], St[1][1]); pv.w = pk2(St[1][2], St[1][3]);
;                     const bf16x8 Pf = __builtin_bit_cast(bf16x8, pv);
; #pragma unroll
;                     for (int db = 0; db < 8; ++db) { const LAS unsigned char* vp = Vt + (db * 16 + fr) * 144 + (ks0 + g * 4) * 2;
;                         const u32x2 lo = *(const LAS u32x2*)(vp), hi = *(const LAS u32x2*)(vp + 32);
.LBB0_247:
	s_movk_i32 s45, 0x1400
	s_add_i32 s4, s18, s94
	v_cmp_ge_u32_e32 vcc, s4, v135
	v_cmp_lt_u32_e64 s[4:5], s4, v137
	s_and_b64 s[40:41], vcc, s[4:5]
	s_waitcnt lgkmcnt(0)
	s_barrier
	s_and_saveexec_b64 s[4:5], s[40:41]
	s_cbranch_execz .LBB0_244
	ds_read_b128 v[116:119], v209
	ds_read_b128 v[120:123], v209 offset:64
	ds_read_b128 v[234:237], v209 offset:128
	ds_read_b128 v[238:241], v209 offset:192
	ds_read_b128 v[242:245], v209 offset:4352
	ds_read_b128 v[212:215], v209 offset:4416
	ds_read_b128 v[246:249], v209 offset:4480
	s_waitcnt lgkmcnt(6)
	v_mfma_f32_16x16x32_bf16 v[116:119], v[116:119], v[4:7], 0
	s_waitcnt lgkmcnt(5)
	v_mfma_f32_16x16x32_bf16 v[116:119], v[120:123], v[8:11], v[116:119]
	s_waitcnt lgkmcnt(4)
	v_mfma_f32_16x16x32_bf16 v[116:119], v[234:237], v[12:15], v[116:119]
	ds_read_b128 v[234:237], v209 offset:4544
	s_waitcnt lgkmcnt(4)
	v_mfma_f32_16x16x32_bf16 v[116:119], v[238:241], v[16:19], v[116:119]
	s_waitcnt lgkmcnt(3)
	v_mfma_f32_16x16x32_bf16 v[120:123], v[242:245], v[4:7], 0
	s_waitcnt lgkmcnt(2)
	v_mfma_f32_16x16x32_bf16 v[120:123], v[212:215], v[8:11], v[120:123]
	s_waitcnt lgkmcnt(1)
	v_mfma_f32_16x16x32_bf16 v[120:123], v[246:249], v[12:15], v[120:123]
	s_waitcnt lgkmcnt(0)
	v_mfma_f32_16x16x32_bf16 v[120:123], v[234:237], v[16:19], v[120:123]
	v_add_u32_e32 v234, v1, v174
	v_add_u32_e32 v235, v1, v175
	v_add_u32_e32 v236, v1, v176
	v_add_u32_e32 v237, v1, v177
	v_add_u32_e32 v238, v1, v195
	v_add_u32_e32 v239, v1, v196
	v_add_u32_e32 v240, v1, v197
	v_add_u32_e32 v241, v1, v198
	ds_read_b32 v234, v234 offset:36892
	ds_read_b32 v235, v235 offset:36892
	ds_read_b32 v236, v236 offset:36892
	ds_read_b32 v237, v237 offset:36892
	ds_read_b32 v238, v238 offset:36892
	ds_read_b32 v239, v239 offset:36892
	ds_read_b32 v240, v240 offset:36892
	ds_read_b32 v241, v241 offset:36892
	v_mov_b32_e32 v248, 0xff800000
	s_waitcnt lgkmcnt(0)
	v_add_f32_e32 v234, v116, v234
	v_add_f32_e32 v235, v117, v235
	v_add_f32_e32 v236, v118, v236
	v_add_f32_e32 v237, v119, v237
	v_add_f32_e32 v238, v120, v238
	v_add_f32_e32 v239, v121, v239
	v_add_f32_e32 v240, v122, v240
	v_add_f32_e32 v241, v123, v241
	v_cndmask_b32_e64 v214, v248, v234, s[8:9]
	v_cndmask_b32_e64 v215, v248, v235, s[10:11]
	v_cndmask_b32_e64 v224, v248, v236, s[12:13]
	v_cndmask_b32_e64 v116, v248, v237, s[24:25]
	v_cndmask_b32_e64 v118, v248, v238, s[26:27]
	v_cndmask_b32_e64 v117, v248, v239, s[28:29]
	v_cndmask_b32_e64 v120, v248, v240, s[30:31]
	v_cndmask_b32_e64 v119, v248, v241, s[34:35]
	v_mov_b32_e32 v213, 0xff800000
	v_max3_f32 v121, v214, v213, v215
	v_max3_f32 v121, v121, v224, v116
	v_max3_f32 v121, v121, v118, v117
	v_max3_f32 v121, v121, v120, v119
	ds_bpermute_b32 v122, v169, v121
	v_add_u32_e32 v220, v167, v144
	s_waitcnt lgkmcnt(0)
	v_max_f32_e32 v122, v122, v122
	v_max_f32_e32 v121, v121, v122
	ds_bpermute_b32 v122, v170, v121
	s_waitcnt lgkmcnt(0)
	v_max3_f32 v212, v142, v121, v122
	v_sub_f32_e32 v116, v116, v212
	v_sub_f32_e32 v122, v214, v212
	v_mul_f32_e32 v116, 0x3fb8aa3b, v116
	v_mul_f32_e32 v122, 0x3fb8aa3b, v122
	v_exp_f32_e32 v225, v116
	v_sub_f32_e32 v116, v118, v212
	v_exp_f32_e32 v214, v122
	v_sub_f32_e32 v122, v215, v212
	v_mul_f32_e32 v116, 0x3fb8aa3b, v116
	v_mul_f32_e32 v122, 0x3fb8aa3b, v122
	v_exp_f32_e32 v226, v116
	v_sub_f32_e32 v116, v117, v212
	v_sub_f32_e32 v121, v142, v212
	v_exp_f32_e32 v215, v122
	v_sub_f32_e32 v122, v224, v212
	v_mul_f32_e32 v116, 0x3fb8aa3b, v116
	v_mul_f32_e32 v121, 0x3fb8aa3b, v121
	v_mul_f32_e32 v122, 0x3fb8aa3b, v122
	v_exp_f32_e32 v227, v116
	v_sub_f32_e32 v116, v120, v212
	v_add_u32_e32 v120, 0x4000, v220
	v_exp_f32_e32 v224, v122
	v_exp_f32_e32 v142, v121
	ds_read2_b64 v[120:123], v120 offset0:128 offset1:132
	v_mul_f32_e32 v116, 0x3fb8aa3b, v116
	v_exp_f32_e32 v228, v116
	v_sub_f32_e32 v116, v119, v212
	v_mul_f32_e32 v116, 0x3fb8aa3b, v116
	v_pk_mul_f32 v[54:55], v[54:55], v[142:143] op_sel_hi:[1,0]
	v_pk_mul_f32 v[52:53], v[52:53], v[142:143] op_sel_hi:[1,0]
	v_exp_f32_e32 v229, v116
	v_cvt_pk_bf16_f32 v116, v214, v215
	v_cvt_pk_bf16_f32 v117, v224, v225
	v_cvt_pk_bf16_f32 v118, v226, v227
	v_cvt_pk_bf16_f32 v119, v228, v229
	v_pk_mul_f32 v[58:59], v[58:59], v[142:143] op_sel_hi:[1,0]
	s_waitcnt lgkmcnt(0)
; #define LAS __attribute__((address_space(3)))
; __device__ __forceinline__ void phase_attn(const Params& p, int l, LAS unsigned char* lds, int bid, int G, int tid) {
;     ...
;                     const int qb = 2 * qh + blk; int ks0 = 16 * qb - 8; ks0 = ks0 < 0 ? 0 : ks0; ks0 = ks0 > 32 ? 32 : ks0;
;                     f32x4 St[2];
; #pragma unroll
;                     for (int nb = 0; nb < 2; ++nb) { f32x4 a0 = {0.f, 0.f, 0.f, 0.f};
; #pragma unroll
;                         for (int ks = 0; ks < 4; ++ks) { const bf16x8 kf = *(const LAS bf16x8*)(Kt + (ks0 + nb * 16 + fr) * 272 + (ks * 32 + g * 8) * 2);
;                             a0 = __builtin_amdgcn_mfma_f32_16x16x32_bf16(kf, Qf[blk][ks], a0, 0, 0, 0); }
;                         St[nb] = a0; }
;                     const int qc = qb * 16 + fr; int cs = qc - 8; cs = cs < 0 ? 0 : cs; cs = cs > 48 ? 48 : cs;
;                     float mt = -INFINITY;
; #pragma unroll
;                     for (int nb = 0; nb < 2; ++nb)
; #pragma unroll
;                         for (int j = 0; j < 4; ++j) { const int kc = ks0 + nb * 16 + g * 4 + j; const bool ok = (kc >= cs) && (kc < cs + 16);
;                             int dc = kc - qc; dc = dc < -15 ? -15 : dc; dc = dc > 15 ? 15 : dc;
;                             const float sv = ok ? St[nb][j] + rp[dc + 15] : -INFINITY; St[nb][j] = sv; mt = fmaxf(mt, sv); }
;                     mt = fmaxf(mt, __shfl_xor(mt, 16)); mt = fmaxf(mt, __shfl_xor(mt, 32));
;                     const float mnew = fmaxf(mrun[blk], mt), alpha = __expf(mrun[blk] - mnew);
;                     float psum = 0.f;
; #pragma unroll
;                     for (int nb = 0; nb < 2; ++nb)
; #pragma unroll
;                         for (int j = 0; j < 4; ++j) { const float pe = __expf(St[nb][j] - mnew); St[nb][j] = pe; psum += pe; }
;                     lrun[blk] = lrun[blk] * alpha + psum; mrun[blk] = mnew;
;                     u32x4 pv; pv.x = pk2(St[0][0], St[0][1]); pv.y = pk2(St[0][2], St[0][3]); pv.z = pk2(St[1][0], St[1][1]); pv.w = pk2(St[1][2], St[1][3]);
;                     const bf16x8 Pf = __builtin_bit_cast(bf16x8, pv);
; #pragma unroll
;                     for (int db = 0; db < 8; ++db) { const LAS unsigned char* vp = Vt + (db * 16 + fr) * 144 + (ks0 + g * 4) * 2;
;                         const u32x2 lo = *(const LAS u32x2*)(vp), hi = *(const LAS u32x2*)(vp + 32);
	v_mfma_f32_16x16x32_bf16 v[52:55], v[120:123], v[116:119], v[52:55]
	v_add_u32_e32 v120, 0x4800, v220
	ds_read2_b64 v[120:123], v120 offset0:160 offset1:164
	v_pk_mul_f32 v[56:57], v[56:57], v[142:143] op_sel_hi:[1,0]
	v_pk_mul_f32 v[62:63], v[62:63], v[142:143] op_sel_hi:[1,0]
	v_pk_mul_f32 v[60:61], v[60:61], v[142:143] op_sel_hi:[1,0]
	s_waitcnt lgkmcnt(0)
	v_mfma_f32_16x16x32_bf16 v[56:59], v[120:123], v[116:119], v[56:59]
	v_add_u32_e32 v120, 0x5000, v220
	ds_read2_b64 v[120:123], v120 offset0:192 offset1:196
	v_pk_mul_f32 v[66:67], v[66:67], v[142:143] op_sel_hi:[1,0]
	s_waitcnt lgkmcnt(0)
	v_mfma_f32_16x16x32_bf16 v[60:63], v[120:123], v[116:119], v[60:63]
	v_add_u32_e32 v120, 0x5800, v220
	ds_read2_b64 v[120:123], v120 offset0:224 offset1:228
	v_pk_mul_f32 v[64:65], v[64:65], v[142:143] op_sel_hi:[1,0]
	v_pk_mul_f32 v[74:75], v[74:75], v[142:143] op_sel_hi:[1,0]
	v_pk_mul_f32 v[72:73], v[72:73], v[142:143] op_sel_hi:[1,0]
	s_waitcnt lgkmcnt(0)
	v_mfma_f32_16x16x32_bf16 v[64:67], v[120:123], v[116:119], v[64:67]
	v_add_u32_e32 v120, 0x6800, v220
	ds_read2_b64 v[120:123], v120 offset1:4
	v_pk_mul_f32 v[82:83], v[82:83], v[142:143] op_sel_hi:[1,0]
	s_waitcnt lgkmcnt(0)
	v_mfma_f32_16x16x32_bf16 v[72:75], v[120:123], v[116:119], v[72:75]
	v_add_u32_e32 v120, 0x7000, v220
	ds_read2_b64 v[120:123], v120 offset0:32 offset1:36
	v_pk_mul_f32 v[80:81], v[80:81], v[142:143] op_sel_hi:[1,0]
	v_pk_mul_f32 v[70:71], v[70:71], v[142:143] op_sel_hi:[1,0]
	v_pk_mul_f32 v[68:69], v[68:69], v[142:143] op_sel_hi:[1,0]
	s_waitcnt lgkmcnt(0)
	v_mfma_f32_16x16x32_bf16 v[80:83], v[120:123], v[116:119], v[80:83]
	v_add_u32_e32 v120, 0x7800, v220
	ds_read2_b64 v[120:123], v120 offset0:64 offset1:68
	v_pk_mul_f32 v[78:79], v[78:79], v[142:143] op_sel_hi:[1,0]
	s_waitcnt lgkmcnt(0)
	v_mfma_f32_16x16x32_bf16 v[68:71], v[120:123], v[116:119], v[68:71]
	v_add_u32_e32 v120, 0x8000, v220
	ds_read2_b64 v[120:123], v120 offset0:96 offset1:100
	v_pk_mul_f32 v[76:77], v[76:77], v[142:143] op_sel_hi:[1,0]
	v_add_u32_e32 v220, v166, v153
	ds_read_b128 v[230:233], v220 offset:4416
	s_waitcnt lgkmcnt(1)
	v_mfma_f32_16x16x32_bf16 v[76:79], v[120:123], v[116:119], v[76:79]
	ds_read_b128 v[116:119], v220
	ds_read_b128 v[120:123], v220 offset:64
	s_waitcnt lgkmcnt(1)
	v_mfma_f32_16x16x32_bf16 v[116:119], v[116:119], v[20:23], 0
	s_waitcnt lgkmcnt(0)
	v_mfma_f32_16x16x32_bf16 v[116:119], v[120:123], v[24:27], v[116:119]
	ds_read_b128 v[120:123], v220 offset:128
	s_waitcnt lgkmcnt(0)
	v_mfma_f32_16x16x32_bf16 v[116:119], v[120:123], v[28:31], v[116:119]
	ds_read_b128 v[120:123], v220 offset:192
	s_waitcnt lgkmcnt(0)
	v_mfma_f32_16x16x32_bf16 v[120:123], v[120:123], v[32:35], v[116:119]
	s_nop 4
	ds_read_b128 v[116:119], v220 offset:4352
	s_waitcnt lgkmcnt(0)
	v_mfma_f32_16x16x32_bf16 v[116:119], v[116:119], v[20:23], 0
	v_mfma_f32_16x16x32_bf16 v[116:119], v[230:233], v[24:27], v[116:119]
	ds_read_b128 v[230:233], v220 offset:4480
	s_waitcnt lgkmcnt(0)
	v_mfma_f32_16x16x32_bf16 v[116:119], v[230:233], v[28:31], v[116:119]
	ds_read_b128 v[230:233], v220 offset:4544
	s_waitcnt lgkmcnt(0)
	v_mfma_f32_16x16x32_bf16 v[116:119], v[230:233], v[32:35], v[116:119]
	v_add_u32_e32 v234, v1, v199
	v_add_u32_e32 v235, v1, v200
	v_add_u32_e32 v236, v1, v201
	v_add_u32_e32 v237, v1, v202
	v_add_u32_e32 v238, v1, v203
	v_add_u32_e32 v239, v1, v204
	v_add_u32_e32 v240, v1, v205
	v_add_u32_e32 v241, v1, v206
	ds_read_b32 v234, v234 offset:36892
	ds_read_b32 v235, v235 offset:36892
	ds_read_b32 v236, v236 offset:36892
	ds_read_b32 v237, v237 offset:36892
	ds_read_b32 v238, v238 offset:36892
	ds_read_b32 v239, v239 offset:36892
	ds_read_b32 v240, v240 offset:36892
	ds_read_b32 v241, v241 offset:36892
	v_mov_b32_e32 v248, 0xff800000
	s_waitcnt lgkmcnt(0)
	v_add_f32_e32 v234, v120, v234
	v_add_f32_e32 v235, v121, v235
	v_add_f32_e32 v236, v122, v236
	v_add_f32_e32 v237, v123, v237
	v_add_f32_e32 v238, v116, v238
	v_add_f32_e32 v239, v117, v239
	v_add_f32_e32 v240, v118, v240
	v_add_f32_e32 v241, v119, v241
	v_cndmask_b32_e64 v230, v248, v234, s[36:37]
	v_cndmask_b32_e64 v213, v248, v235, s[48:49]
	v_cndmask_b32_e64 v231, v248, v236, s[74:75]
	v_cndmask_b32_e64 v120, v248, v237, s[76:77]
	v_cndmask_b32_e64 v123, v248, v238, s[78:79]
	v_cndmask_b32_e64 v122, v248, v239, s[82:83]
	v_cndmask_b32_e64 v117, v248, v240, s[84:85]
	v_cndmask_b32_e64 v116, v248, v241, s[86:87]
	s_mov_b64 s[40:41], exec
	s_branch .LBB0_243
